# P7 GEMM mainloop: hipcc per-phase s_setprio flips removed, one static s_setprio 1 for waves 4-7 before the K loop
# speedup vs baseline: 1.1189x; 1.0043x over previous
; #define PG8_STAGE(bufoff, gbase, voff) do { _Pragma("unroll") for (int _i = 0; _i < 2; ++_i) \
;         __builtin_amdgcn_global_load_lds((const unsigned*)((const char*)(gbase) + (voff)[_i]), (LAS unsigned*)(lds + (bufoff) + ldsw + _i * 8192), 16, 0, 0); } while (0)
; #define PG8_LDA(dst, b, h) do { _Pragma("unroll") for (int m = 0; m < 4; ++m) _Pragma("unroll") for (int k = 0; k < 2; ++k) dst[m][k] = *(const LAS bf16x8*)(lds + PG8_SA(b, h) + aoff + m * 2048 + k * 1024); } while (0)
; #define PG8_LDB(dst, b, h) do { _Pragma("unroll") for (int n = 0; n < 2; ++n) _Pragma("unroll") for (int k = 0; k < 2; ++k) dst[n][k] = *(const LAS bf16x8*)(lds + PG8_SB(b, h) + boff + n * 2048 + k * 1024); } while (0)
; #define PG8_WAIT_L(n) asm volatile("s_waitcnt lgkmcnt(" #n ")" ::: "memory")
; #define PG8_BAR __builtin_amdgcn_s_barrier()
; #define PG8_SCHED __builtin_amdgcn_sched_barrier(0)
; template <class Epi, class Sched>
; __device__ __forceinline__ void gemm_phase(LAS unsigned char* lds, const Gemm g, const Sched& S, const Epi& E) {
;     ...
;     for (;;) {
;         const bool has_next = S.next(ui + 1, nxt);
;         const char* nA = has_next ? (const char*)g.A + (size_t)nxt.pm * tstepA + (size_t)nxt.koffA * 2 : cA; const char* nB = has_next ? (const char*)g.Bt + (size_t)nxt.pn * tstepB + (size_t)nxt.koffB * 2 : cB;
; #pragma clang loop unroll(disable)
;         for (int t = 0; t < nt; t += 2) {
;             const bool last = (t == nt - 2);
;             const char* a1 = cA + (size_t)(t + 1) * kstep;
;             const char* a2 = last ? nA : cA + (size_t)(t + 2) * kstep; const char* b2 = last ? nB : cB + (size_t)(t + 2) * kstep;
;             const char* a3 = a2 + kstep; const char* b3 = b2 + kstep;
;             PG8_LDB(B0, 0, 0); PG8_SCHED; PG8_LDA(At, 0, 0); PG8_STAGE(PG8_SA(1, 1), a1 + hstepA, voffA);
;             PG8_WAIT_L(8); PG8_BAR; PG8_WAIT_L(0); PG8_MMA(0, 0, At, B0); PG8_BAR; PG8_SCHED;
;     ...
; #pragma unroll
;         for (int a = 0; a < 2; ++a)
; #pragma unroll
;             for (int b = 0; b < 2; ++b)
; #pragma unroll
;                 for (int m = 0; m < 4; ++m)
; #pragma unroll
;                     for (int n = 0; n < 2; ++n) acc[a][b][m][n] = (f32x4){0.f, 0.f, 0.f, 0.f};
;         cur = nxt; cA = nA; cB = nB; ++ui;
.LBB0_1208:
	s_ashr_i32 s11, s10, 31
	v_cmp_lt_i64_e32 vcc, s[4:5], v[140:141]
	s_lshl_b64 s[4:5], s[10:11], 20
	s_add_u32 s12, s46, s4
	s_addc_u32 s13, s47, s5
	s_and_b64 s[4:5], vcc, exec
	s_cselect_b32 s4, s13, s25
	s_cselect_b32 s5, s12, s24
	s_ashr_i32 s9, s8, 31
	s_lshl_b64 s[16:17], s[8:9], 20
	s_add_u32 s16, s20, s16
	s_addc_u32 s17, s21, s17
	s_and_b64 s[36:37], vcc, exec
	s_cselect_b32 s9, s17, s27
	s_cselect_b32 s11, s16, s26
	s_add_u32 s24, s24, 0x80080
	s_addc_u32 s25, s25, 0
	s_add_u32 s43, s26, 0x100
	v_mov_b32_e32 v0, 0
	s_addc_u32 s44, s27, 0
	s_mov_b32 s45, -2
	v_mov_b32_e32 v1, v0
	v_mov_b32_e32 v2, v0
	v_mov_b32_e32 v3, v0
	v_mov_b32_e32 v8, v0
	v_mov_b32_e32 v9, v0
	v_mov_b32_e32 v10, v0
	v_mov_b32_e32 v11, v0
	v_mov_b32_e32 v16, v0
	v_mov_b32_e32 v17, v0
	v_mov_b32_e32 v18, v0
	v_mov_b32_e32 v19, v0
	v_mov_b32_e32 v24, v0
	v_mov_b32_e32 v25, v0
	v_mov_b32_e32 v26, v0
	v_mov_b32_e32 v27, v0
	v_mov_b32_e32 v32, v0
	v_mov_b32_e32 v33, v0
	v_mov_b32_e32 v34, v0
	v_mov_b32_e32 v35, v0
	v_mov_b32_e32 v40, v0
	v_mov_b32_e32 v41, v0
	v_mov_b32_e32 v42, v0
	v_mov_b32_e32 v43, v0
	v_mov_b32_e32 v48, v0
	v_mov_b32_e32 v49, v0
	v_mov_b32_e32 v50, v0
	v_mov_b32_e32 v51, v0
	v_mov_b32_e32 v56, v0
	v_mov_b32_e32 v57, v0
	v_mov_b32_e32 v58, v0
	v_mov_b32_e32 v59, v0
	v_mov_b32_e32 v4, v0
	v_mov_b32_e32 v5, v0
	v_mov_b32_e32 v6, v0
	v_mov_b32_e32 v7, v0
	v_mov_b32_e32 v12, v0
	v_mov_b32_e32 v13, v0
	v_mov_b32_e32 v14, v0
	v_mov_b32_e32 v15, v0
	v_mov_b32_e32 v20, v0
	v_mov_b32_e32 v21, v0
	v_mov_b32_e32 v22, v0
	v_mov_b32_e32 v23, v0
	v_mov_b32_e32 v28, v0
	v_mov_b32_e32 v29, v0
	v_mov_b32_e32 v30, v0
	v_mov_b32_e32 v31, v0
	v_mov_b32_e32 v36, v0
	v_mov_b32_e32 v37, v0
	v_mov_b32_e32 v38, v0
	v_mov_b32_e32 v39, v0
	v_mov_b32_e32 v44, v0
	v_mov_b32_e32 v45, v0
	v_mov_b32_e32 v46, v0
	v_mov_b32_e32 v47, v0
	v_mov_b32_e32 v52, v0
	v_mov_b32_e32 v53, v0
	v_mov_b32_e32 v54, v0
	v_mov_b32_e32 v55, v0
	v_mov_b32_e32 v60, v0
	v_mov_b32_e32 v61, v0
	v_mov_b32_e32 v62, v0
	v_mov_b32_e32 v63, v0
	v_mov_b32_e32 v64, v0
	v_mov_b32_e32 v65, v0
	v_mov_b32_e32 v66, v0
	v_mov_b32_e32 v67, v0
	v_mov_b32_e32 v72, v0
	v_mov_b32_e32 v73, v0
	v_mov_b32_e32 v74, v0
	v_mov_b32_e32 v75, v0
	v_mov_b32_e32 v80, v0
	v_mov_b32_e32 v81, v0
	v_mov_b32_e32 v82, v0
	v_mov_b32_e32 v83, v0
	v_mov_b32_e32 v88, v0
	v_mov_b32_e32 v89, v0
	v_mov_b32_e32 v90, v0
	v_mov_b32_e32 v91, v0
	v_mov_b32_e32 v96, v0
	v_mov_b32_e32 v97, v0
	v_mov_b32_e32 v98, v0
	v_mov_b32_e32 v99, v0
	v_mov_b32_e32 v104, v0
	v_mov_b32_e32 v105, v0
	v_mov_b32_e32 v106, v0
	v_mov_b32_e32 v107, v0
	v_mov_b32_e32 v120, v0
	v_mov_b32_e32 v121, v0
	v_mov_b32_e32 v122, v0
	v_mov_b32_e32 v123, v0
	v_mov_b32_e32 v124, v0
	v_mov_b32_e32 v125, v0
	v_mov_b32_e32 v126, v0
	v_mov_b32_e32 v127, v0
	v_mov_b32_e32 v68, v0
	v_mov_b32_e32 v69, v0
	v_mov_b32_e32 v70, v0
	v_mov_b32_e32 v71, v0
	v_mov_b32_e32 v76, v0
	v_mov_b32_e32 v77, v0
	v_mov_b32_e32 v78, v0
	v_mov_b32_e32 v79, v0
	v_mov_b32_e32 v84, v0
	v_mov_b32_e32 v85, v0
	v_mov_b32_e32 v86, v0
	v_mov_b32_e32 v87, v0
	v_mov_b32_e32 v92, v0
	v_mov_b32_e32 v93, v0
	v_mov_b32_e32 v94, v0
	v_mov_b32_e32 v95, v0
	v_mov_b32_e32 v100, v0
	v_mov_b32_e32 v101, v0
	v_mov_b32_e32 v102, v0
	v_mov_b32_e32 v103, v0
	v_mov_b32_e32 v108, v0
	v_mov_b32_e32 v109, v0
	v_mov_b32_e32 v110, v0
	v_mov_b32_e32 v111, v0
	v_mov_b32_e32 v112, v0
	v_mov_b32_e32 v113, v0
	v_mov_b32_e32 v114, v0
	v_mov_b32_e32 v115, v0
	v_mov_b32_e32 v116, v0
	v_mov_b32_e32 v117, v0
	v_mov_b32_e32 v118, v0
	v_mov_b32_e32 v119, v0
	v_readfirstlane_b32 vcc_lo, v196
	s_nop 3
	s_lshr_b32 vcc_lo, vcc_lo, 8
	s_cmp_lg_u32 vcc_lo, 0
	s_cbranch_scc0 .Lp7_prio_done
	s_setprio 1
.Lp7_prio_done:
.LBB0_1209:
	ds_read_b128 v[152:155], v147
	ds_read_b128 v[156:159], v147 offset:1024
	ds_read_b128 v[160:163], v147 offset:2048
	ds_read_b128 v[164:167], v147 offset:3072
	s_add_u32 s26, s24, 0xfff80080
	s_addc_u32 s27, s25, -1
	s_cmp_eq_u32 s45, 28
	s_cselect_b32 s37, s4, s27
	s_cselect_b32 s36, s5, s26
	s_cselect_b32 s27, s9, s44
	s_cselect_b32 s26, s11, s43
	v_lshl_add_u64 v[202:203], s[24:25], 0, v[136:137]
	s_add_i32 m0, s19, 0xc000
	ds_read_b128 v[168:171], v148
	ds_read_b128 v[172:175], v148 offset:1024
	ds_read_b128 v[176:179], v148 offset:2048
	ds_read_b128 v[180:183], v148 offset:3072
	ds_read_b128 v[184:187], v148 offset:4096
	ds_read_b128 v[188:191], v148 offset:5120
	ds_read_b128 v[192:195], v148 offset:6144
	ds_read_b128 v[198:201], v148 offset:7168
	global_load_lds_dwordx4 v[202:203], off
	v_lshl_add_u64 v[202:203], s[24:25], 0, v[138:139]
	s_add_i32 m0, s19, 0xe000
	s_nop 0
	global_load_lds_dwordx4 v[202:203], off
	s_waitcnt lgkmcnt(8)
	s_barrier
	s_waitcnt lgkmcnt(0)
	s_waitcnt lgkmcnt(0)
	v_mfma_f32_16x16x32_bf16 v[116:119], v[152:155], v[168:171], v[116:119]
	v_mfma_f32_16x16x32_bf16 v[112:115], v[160:163], v[168:171], v[112:115]
	v_mfma_f32_16x16x32_bf16 v[108:111], v[152:155], v[176:179], v[108:111]
	v_mfma_f32_16x16x32_bf16 v[100:103], v[160:163], v[176:179], v[100:103]
	v_mfma_f32_16x16x32_bf16 v[92:95], v[152:155], v[184:187], v[92:95]
	v_mfma_f32_16x16x32_bf16 v[84:87], v[160:163], v[184:187], v[84:87]
	v_mfma_f32_16x16x32_bf16 v[76:79], v[152:155], v[192:195], v[76:79]
	v_mfma_f32_16x16x32_bf16 v[68:71], v[160:163], v[192:195], v[68:71]
	v_mfma_f32_16x16x32_bf16 v[116:119], v[156:159], v[172:175], v[116:119]
	v_mfma_f32_16x16x32_bf16 v[112:115], v[164:167], v[172:175], v[112:115]
	v_mfma_f32_16x16x32_bf16 v[108:111], v[156:159], v[180:183], v[108:111]
	v_mfma_f32_16x16x32_bf16 v[100:103], v[164:167], v[180:183], v[100:103]
	v_mfma_f32_16x16x32_bf16 v[92:95], v[156:159], v[188:191], v[92:95]
	v_mfma_f32_16x16x32_bf16 v[84:87], v[164:167], v[188:191], v[84:87]
	v_mfma_f32_16x16x32_bf16 v[76:79], v[156:159], v[198:201], v[76:79]
	v_mfma_f32_16x16x32_bf16 v[68:71], v[164:167], v[198:201], v[68:71]
	s_barrier
; #define PG8_STAGE(bufoff, gbase, voff) do { _Pragma("unroll") for (int _i = 0; _i < 2; ++_i) \
;         __builtin_amdgcn_global_load_lds((const unsigned*)((const char*)(gbase) + (voff)[_i]), (LAS unsigned*)(lds + (bufoff) + ldsw + _i * 8192), 16, 0, 0); } while (0)
; #define PG8_LDA(dst, b, h) do { _Pragma("unroll") for (int m = 0; m < 4; ++m) _Pragma("unroll") for (int k = 0; k < 2; ++k) dst[m][k] = *(const LAS bf16x8*)(lds + PG8_SA(b, h) + aoff + m * 2048 + k * 1024); } while (0)
; #define PG8_LDB(dst, b, h) do { _Pragma("unroll") for (int n = 0; n < 2; ++n) _Pragma("unroll") for (int k = 0; k < 2; ++k) dst[n][k] = *(const LAS bf16x8*)(lds + PG8_SB(b, h) + boff + n * 2048 + k * 1024); } while (0)
; #define PG8_WAIT_V(n) asm volatile("s_waitcnt vmcnt(" #n ")" ::: "memory")
; #define PG8_WAIT_L(n) asm volatile("s_waitcnt lgkmcnt(" #n ")" ::: "memory")
; #define PG8_BAR __builtin_amdgcn_s_barrier()
; #define PG8_SCHED __builtin_amdgcn_sched_barrier(0)
; template <class Epi, class Sched>
; __device__ __forceinline__ void gemm_phase(LAS unsigned char* lds, const Gemm g, const Sched& S, const Epi& E) {
;     ...
;             PG8_LDB(B0, 0, 0); PG8_SCHED; PG8_LDA(At, 0, 0); PG8_STAGE(PG8_SA(1, 1), a1 + hstepA, voffA);
;             PG8_WAIT_L(8); PG8_BAR; PG8_WAIT_L(0); PG8_MMA(0, 0, At, B0); PG8_BAR; PG8_SCHED;
;             PG8_LDB(B1, 0, 1); PG8_STAGE(PG8_SB(0, 0), b2, voffB);
;             PG8_BAR; PG8_WAIT_L(0); PG8_MMA(0, 1, At, B1); PG8_BAR;
;             PG8_LDA(At, 0, 1); PG8_STAGE(PG8_SA(0, 0), a2, voffA);
;             PG8_BAR; PG8_WAIT_L(0); PG8_MMA(1, 0, At, B0); PG8_BAR; PG8_SCHED;
;             PG8_STAGE(PG8_SB(0, 1), b2 + hstepB, voffB);
;             PG8_WAIT_V(6); PG8_BAR; PG8_MMA(1, 1, At, B1); PG8_BAR;
;             PG8_LDB(B0, 1, 0); PG8_SCHED; PG8_LDA(At, 1, 0); PG8_STAGE(PG8_SA(0, 1), a2 + hstepA, voffA);
;             PG8_WAIT_L(8); PG8_BAR; PG8_WAIT_L(0); PG8_MMA(0, 0, At, B0); PG8_BAR; PG8_SCHED;
;             PG8_LDB(B1, 1, 1); PG8_STAGE(PG8_SB(1, 0), b3, voffB);
;             PG8_BAR; PG8_WAIT_L(0); PG8_MMA(0, 1, At, B1); PG8_BAR;
;             PG8_LDA(At, 1, 1); PG8_STAGE(PG8_SA(1, 0), a3, voffA);
;             PG8_BAR; PG8_WAIT_L(0); PG8_MMA(1, 0, At, B0); PG8_BAR; PG8_SCHED;
;             PG8_STAGE(PG8_SB(1, 1), b3 + hstepB, voffB);
;             PG8_WAIT_V(6); PG8_BAR; PG8_MMA(1, 1, At, B1); PG8_BAR;
	s_add_i32 s50, s38, s22
	v_lshl_add_u64 v[218:219], s[26:27], 0, v[130:131]
	s_mov_b32 m0, s50
	ds_read_b128 v[202:205], v149
	ds_read_b128 v[206:209], v149 offset:1024
	ds_read_b128 v[210:213], v149 offset:2048
	ds_read_b128 v[214:217], v149 offset:3072
	global_load_lds_dwordx4 v[218:219], off
	v_lshl_add_u64 v[220:221], s[26:27], 0, v[134:135]
	s_add_i32 m0, s50, 0x2000
	s_nop 0
	global_load_lds_dwordx4 v[220:221], off
	s_barrier
	s_waitcnt lgkmcnt(0)
	s_waitcnt lgkmcnt(0)
	v_mfma_f32_16x16x32_bf16 v[124:127], v[202:205], v[168:171], v[124:127]
	v_mfma_f32_16x16x32_bf16 v[120:123], v[210:213], v[168:171], v[120:123]
	v_mfma_f32_16x16x32_bf16 v[104:107], v[202:205], v[176:179], v[104:107]
	v_mfma_f32_16x16x32_bf16 v[96:99], v[210:213], v[176:179], v[96:99]
	v_mfma_f32_16x16x32_bf16 v[88:91], v[202:205], v[184:187], v[88:91]
	v_mfma_f32_16x16x32_bf16 v[80:83], v[210:213], v[184:187], v[80:83]
	v_mfma_f32_16x16x32_bf16 v[72:75], v[202:205], v[192:195], v[72:75]
	v_mfma_f32_16x16x32_bf16 v[64:67], v[210:213], v[192:195], v[64:67]
	v_mfma_f32_16x16x32_bf16 v[124:127], v[206:209], v[172:175], v[124:127]
	v_mfma_f32_16x16x32_bf16 v[120:123], v[214:217], v[172:175], v[120:123]
	v_mfma_f32_16x16x32_bf16 v[104:107], v[206:209], v[180:183], v[104:107]
	v_mfma_f32_16x16x32_bf16 v[96:99], v[214:217], v[180:183], v[96:99]
	v_mfma_f32_16x16x32_bf16 v[88:91], v[206:209], v[188:191], v[88:91]
	v_mfma_f32_16x16x32_bf16 v[80:83], v[214:217], v[188:191], v[80:83]
	v_mfma_f32_16x16x32_bf16 v[72:75], v[206:209], v[198:201], v[72:75]
	v_mfma_f32_16x16x32_bf16 v[64:67], v[214:217], v[198:201], v[64:67]
	s_mov_b32 m0, s19
	v_lshl_add_u64 v[222:223], s[36:37], 0, v[128:129]
	s_barrier
	ds_read_b128 v[168:171], v148 offset:16384
	ds_read_b128 v[172:175], v148 offset:17408
	ds_read_b128 v[176:179], v148 offset:18432
	ds_read_b128 v[180:183], v148 offset:19456
	ds_read_b128 v[184:187], v148 offset:20480
	ds_read_b128 v[188:191], v148 offset:21504
	ds_read_b128 v[192:195], v148 offset:22528
	ds_read_b128 v[198:201], v148 offset:23552
	global_load_lds_dwordx4 v[222:223], off
	v_lshl_add_u64 v[224:225], s[36:37], 0, v[132:133]
	s_mov_b32 m0, s23
	s_nop 0
	global_load_lds_dwordx4 v[224:225], off
	s_barrier
	s_waitcnt lgkmcnt(0)
	s_waitcnt lgkmcnt(0)
	v_mfma_f32_16x16x32_bf16 v[60:63], v[152:155], v[168:171], v[60:63]
	v_mfma_f32_16x16x32_bf16 v[52:55], v[160:163], v[168:171], v[52:55]
	v_mfma_f32_16x16x32_bf16 v[44:47], v[152:155], v[176:179], v[44:47]
	v_mfma_f32_16x16x32_bf16 v[36:39], v[160:163], v[176:179], v[36:39]
	v_mfma_f32_16x16x32_bf16 v[28:31], v[152:155], v[184:187], v[28:31]
	v_mfma_f32_16x16x32_bf16 v[20:23], v[160:163], v[184:187], v[20:23]
	v_mfma_f32_16x16x32_bf16 v[12:15], v[152:155], v[192:195], v[12:15]
	v_mfma_f32_16x16x32_bf16 v[4:7], v[160:163], v[192:195], v[4:7]
	v_mfma_f32_16x16x32_bf16 v[60:63], v[156:159], v[172:175], v[60:63]
	v_mfma_f32_16x16x32_bf16 v[52:55], v[164:167], v[172:175], v[52:55]
	v_mfma_f32_16x16x32_bf16 v[44:47], v[156:159], v[180:183], v[44:47]
	v_mfma_f32_16x16x32_bf16 v[36:39], v[164:167], v[180:183], v[36:39]
	v_mfma_f32_16x16x32_bf16 v[28:31], v[156:159], v[188:191], v[28:31]
	v_mfma_f32_16x16x32_bf16 v[20:23], v[164:167], v[188:191], v[20:23]
	v_mfma_f32_16x16x32_bf16 v[12:15], v[156:159], v[198:201], v[12:15]
	v_mfma_f32_16x16x32_bf16 v[4:7], v[164:167], v[198:201], v[4:7]
	s_barrier
	s_add_u32 s50, s26, 0x80000
	s_addc_u32 s51, s27, 0
	s_add_i32 s52, s39, s22
	v_lshl_add_u64 v[152:153], s[50:51], 0, v[130:131]
	s_mov_b32 m0, s52
	s_nop 0
	global_load_lds_dwordx4 v[152:153], off
	v_lshl_add_u64 v[152:153], s[50:51], 0, v[134:135]
	s_add_i32 m0, s52, 0x2000
	s_nop 0
	global_load_lds_dwordx4 v[152:153], off
	s_waitcnt vmcnt(6)
	s_barrier
	v_mfma_f32_16x16x32_bf16 v[56:59], v[202:205], v[168:171], v[56:59]
	v_mfma_f32_16x16x32_bf16 v[48:51], v[210:213], v[168:171], v[48:51]
	v_mfma_f32_16x16x32_bf16 v[40:43], v[202:205], v[176:179], v[40:43]
	v_mfma_f32_16x16x32_bf16 v[32:35], v[210:213], v[176:179], v[32:35]
	v_mfma_f32_16x16x32_bf16 v[24:27], v[202:205], v[184:187], v[24:27]
	v_mfma_f32_16x16x32_bf16 v[16:19], v[210:213], v[184:187], v[16:19]
	v_mfma_f32_16x16x32_bf16 v[8:11], v[202:205], v[192:195], v[8:11]
	v_mfma_f32_16x16x32_bf16 v[0:3], v[210:213], v[192:195], v[0:3]
	v_mfma_f32_16x16x32_bf16 v[56:59], v[206:209], v[172:175], v[56:59]
	v_mfma_f32_16x16x32_bf16 v[48:51], v[214:217], v[172:175], v[48:51]
	v_mfma_f32_16x16x32_bf16 v[40:43], v[206:209], v[180:183], v[40:43]
	v_mfma_f32_16x16x32_bf16 v[32:35], v[214:217], v[180:183], v[32:35]
	v_mfma_f32_16x16x32_bf16 v[24:27], v[206:209], v[188:191], v[24:27]
	v_mfma_f32_16x16x32_bf16 v[16:19], v[214:217], v[188:191], v[16:19]
	v_mfma_f32_16x16x32_bf16 v[8:11], v[206:209], v[198:201], v[8:11]
	v_mfma_f32_16x16x32_bf16 v[0:3], v[214:217], v[198:201], v[0:3]
	s_add_i32 s50, 0, 0x18000
	v_add_u32_e32 v151, s50, v145
	s_barrier
	ds_read_b128 v[152:155], v151
	ds_read_b128 v[156:159], v151 offset:1024
	ds_read_b128 v[160:163], v151 offset:2048
	ds_read_b128 v[164:167], v151 offset:3072
	s_add_u32 s36, s36, 0x80000
	s_addc_u32 s37, s37, 0
	s_mov_b32 m0, s29
	v_lshl_add_u64 v[202:203], s[36:37], 0, v[128:129]
	ds_read_b128 v[168:171], v148 offset:32768
	ds_read_b128 v[172:175], v148 offset:33792
	ds_read_b128 v[176:179], v148 offset:34816
	ds_read_b128 v[180:183], v148 offset:35840
	ds_read_b128 v[184:187], v148 offset:36864
	ds_read_b128 v[188:191], v148 offset:37888
	ds_read_b128 v[192:195], v148 offset:38912
	ds_read_b128 v[198:201], v148 offset:39936
	global_load_lds_dwordx4 v[202:203], off
	v_lshl_add_u64 v[202:203], s[36:37], 0, v[132:133]
	s_mov_b32 m0, s30
	s_nop 0
	global_load_lds_dwordx4 v[202:203], off
	s_waitcnt lgkmcnt(8)
	s_barrier
; #define PG8_STAGE(bufoff, gbase, voff) do { _Pragma("unroll") for (int _i = 0; _i < 2; ++_i) \
;         __builtin_amdgcn_global_load_lds((const unsigned*)((const char*)(gbase) + (voff)[_i]), (LAS unsigned*)(lds + (bufoff) + ldsw + _i * 8192), 16, 0, 0); } while (0)
; #define PG8_LDA(dst, b, h) do { _Pragma("unroll") for (int m = 0; m < 4; ++m) _Pragma("unroll") for (int k = 0; k < 2; ++k) dst[m][k] = *(const LAS bf16x8*)(lds + PG8_SA(b, h) + aoff + m * 2048 + k * 1024); } while (0)
; #define PG8_LDB(dst, b, h) do { _Pragma("unroll") for (int n = 0; n < 2; ++n) _Pragma("unroll") for (int k = 0; k < 2; ++k) dst[n][k] = *(const LAS bf16x8*)(lds + PG8_SB(b, h) + boff + n * 2048 + k * 1024); } while (0)
; #define PG8_WAIT_V(n) asm volatile("s_waitcnt vmcnt(" #n ")" ::: "memory")
; #define PG8_WAIT_L(n) asm volatile("s_waitcnt lgkmcnt(" #n ")" ::: "memory")
; #define PG8_BAR __builtin_amdgcn_s_barrier()
; #define PG8_SCHED __builtin_amdgcn_sched_barrier(0)
; template <class Epi, class Sched>
; __device__ __forceinline__ void gemm_phase(LAS unsigned char* lds, const Gemm g, const Sched& S, const Epi& E) {
;     ...
;             PG8_LDB(B0, 0, 0); PG8_SCHED; PG8_LDA(At, 0, 0); PG8_STAGE(PG8_SA(1, 1), a1 + hstepA, voffA);
;             PG8_WAIT_L(8); PG8_BAR; PG8_WAIT_L(0); PG8_MMA(0, 0, At, B0); PG8_BAR; PG8_SCHED;
;             PG8_LDB(B1, 0, 1); PG8_STAGE(PG8_SB(0, 0), b2, voffB);
;             PG8_BAR; PG8_WAIT_L(0); PG8_MMA(0, 1, At, B1); PG8_BAR;
;             PG8_LDA(At, 0, 1); PG8_STAGE(PG8_SA(0, 0), a2, voffA);
;             PG8_BAR; PG8_WAIT_L(0); PG8_MMA(1, 0, At, B0); PG8_BAR; PG8_SCHED;
;             PG8_STAGE(PG8_SB(0, 1), b2 + hstepB, voffB);
;             PG8_WAIT_V(6); PG8_BAR; PG8_MMA(1, 1, At, B1); PG8_BAR;
;             PG8_LDB(B0, 1, 0); PG8_SCHED; PG8_LDA(At, 1, 0); PG8_STAGE(PG8_SA(0, 1), a2 + hstepA, voffA);
;             PG8_WAIT_L(8); PG8_BAR; PG8_WAIT_L(0); PG8_MMA(0, 0, At, B0); PG8_BAR; PG8_SCHED;
;             PG8_LDB(B1, 1, 1); PG8_STAGE(PG8_SB(1, 0), b3, voffB);
;             PG8_BAR; PG8_WAIT_L(0); PG8_MMA(0, 1, At, B1); PG8_BAR;
;             PG8_LDA(At, 1, 1); PG8_STAGE(PG8_SA(1, 0), a3, voffA);
;             PG8_BAR; PG8_WAIT_L(0); PG8_MMA(1, 0, At, B0); PG8_BAR; PG8_SCHED;
;             PG8_STAGE(PG8_SB(1, 1), b3 + hstepB, voffB);
;             PG8_WAIT_V(6); PG8_BAR; PG8_MMA(1, 1, At, B1); PG8_BAR;
	s_waitcnt lgkmcnt(0)
	s_waitcnt lgkmcnt(0)
	v_mfma_f32_16x16x32_bf16 v[116:119], v[152:155], v[168:171], v[116:119]
	v_mfma_f32_16x16x32_bf16 v[112:115], v[160:163], v[168:171], v[112:115]
	v_mfma_f32_16x16x32_bf16 v[108:111], v[152:155], v[176:179], v[108:111]
	v_mfma_f32_16x16x32_bf16 v[100:103], v[160:163], v[176:179], v[100:103]
	v_mfma_f32_16x16x32_bf16 v[92:95], v[152:155], v[184:187], v[92:95]
	v_mfma_f32_16x16x32_bf16 v[84:87], v[160:163], v[184:187], v[84:87]
	v_mfma_f32_16x16x32_bf16 v[76:79], v[152:155], v[192:195], v[76:79]
	v_mfma_f32_16x16x32_bf16 v[68:71], v[160:163], v[192:195], v[68:71]
	v_mfma_f32_16x16x32_bf16 v[116:119], v[156:159], v[172:175], v[116:119]
	v_mfma_f32_16x16x32_bf16 v[112:115], v[164:167], v[172:175], v[112:115]
	v_mfma_f32_16x16x32_bf16 v[108:111], v[156:159], v[180:183], v[108:111]
	v_mfma_f32_16x16x32_bf16 v[100:103], v[164:167], v[180:183], v[100:103]
	v_mfma_f32_16x16x32_bf16 v[92:95], v[156:159], v[188:191], v[92:95]
	v_mfma_f32_16x16x32_bf16 v[84:87], v[164:167], v[188:191], v[84:87]
	v_mfma_f32_16x16x32_bf16 v[76:79], v[156:159], v[198:201], v[76:79]
	v_mfma_f32_16x16x32_bf16 v[68:71], v[164:167], v[198:201], v[68:71]
	s_barrier
	s_add_i32 s36, 0, 0x1c000
	s_add_i32 s37, s50, s22
	v_add_u32_e32 v151, s36, v145
	v_lshl_add_u64 v[218:219], v[218:219], 0, s[6:7]
	s_mov_b32 m0, s37
	ds_read_b128 v[202:205], v151
	ds_read_b128 v[206:209], v151 offset:1024
	ds_read_b128 v[210:213], v151 offset:2048
	ds_read_b128 v[214:217], v151 offset:3072
	global_load_lds_dwordx4 v[218:219], off
	v_lshl_add_u64 v[218:219], v[220:221], 0, s[6:7]
	s_add_i32 m0, s37, 0x2000
	s_nop 0
	global_load_lds_dwordx4 v[218:219], off
	s_barrier
	s_waitcnt lgkmcnt(0)
	s_waitcnt lgkmcnt(0)
	v_mfma_f32_16x16x32_bf16 v[124:127], v[202:205], v[168:171], v[124:127]
	v_mfma_f32_16x16x32_bf16 v[120:123], v[210:213], v[168:171], v[120:123]
	v_mfma_f32_16x16x32_bf16 v[104:107], v[202:205], v[176:179], v[104:107]
	v_mfma_f32_16x16x32_bf16 v[96:99], v[210:213], v[176:179], v[96:99]
	v_mfma_f32_16x16x32_bf16 v[88:91], v[202:205], v[184:187], v[88:91]
	v_mfma_f32_16x16x32_bf16 v[80:83], v[210:213], v[184:187], v[80:83]
	v_mfma_f32_16x16x32_bf16 v[72:75], v[202:205], v[192:195], v[72:75]
	v_mfma_f32_16x16x32_bf16 v[64:67], v[210:213], v[192:195], v[64:67]
	v_mfma_f32_16x16x32_bf16 v[124:127], v[206:209], v[172:175], v[124:127]
	v_mfma_f32_16x16x32_bf16 v[120:123], v[214:217], v[172:175], v[120:123]
	v_mfma_f32_16x16x32_bf16 v[104:107], v[206:209], v[180:183], v[104:107]
	v_mfma_f32_16x16x32_bf16 v[96:99], v[214:217], v[180:183], v[96:99]
	v_mfma_f32_16x16x32_bf16 v[88:91], v[206:209], v[188:191], v[88:91]
	v_mfma_f32_16x16x32_bf16 v[80:83], v[214:217], v[188:191], v[80:83]
	v_mfma_f32_16x16x32_bf16 v[72:75], v[206:209], v[198:201], v[72:75]
	v_mfma_f32_16x16x32_bf16 v[64:67], v[214:217], v[198:201], v[64:67]
	s_mov_b32 m0, s33
	v_lshl_add_u64 v[218:219], v[222:223], 0, s[6:7]
	s_barrier
	ds_read_b128 v[168:171], v148 offset:49152
	ds_read_b128 v[172:175], v148 offset:50176
	ds_read_b128 v[176:179], v148 offset:51200
	ds_read_b128 v[180:183], v148 offset:52224
	ds_read_b128 v[184:187], v148 offset:53248
	ds_read_b128 v[188:191], v148 offset:54272
	ds_read_b128 v[192:195], v148 offset:55296
	ds_read_b128 v[198:201], v148 offset:56320
	global_load_lds_dwordx4 v[218:219], off
	v_lshl_add_u64 v[218:219], v[224:225], 0, s[6:7]
	s_mov_b32 m0, s34
	s_nop 0
	global_load_lds_dwordx4 v[218:219], off
	s_barrier
	s_waitcnt lgkmcnt(0)
	s_waitcnt lgkmcnt(0)
	v_mfma_f32_16x16x32_bf16 v[60:63], v[152:155], v[168:171], v[60:63]
	v_mfma_f32_16x16x32_bf16 v[52:55], v[160:163], v[168:171], v[52:55]
	v_mfma_f32_16x16x32_bf16 v[44:47], v[152:155], v[176:179], v[44:47]
	v_mfma_f32_16x16x32_bf16 v[36:39], v[160:163], v[176:179], v[36:39]
	v_mfma_f32_16x16x32_bf16 v[28:31], v[152:155], v[184:187], v[28:31]
	v_mfma_f32_16x16x32_bf16 v[20:23], v[160:163], v[184:187], v[20:23]
	v_mfma_f32_16x16x32_bf16 v[12:15], v[152:155], v[192:195], v[12:15]
	v_mfma_f32_16x16x32_bf16 v[4:7], v[160:163], v[192:195], v[4:7]
	v_mfma_f32_16x16x32_bf16 v[60:63], v[156:159], v[172:175], v[60:63]
	v_mfma_f32_16x16x32_bf16 v[52:55], v[164:167], v[172:175], v[52:55]
	v_mfma_f32_16x16x32_bf16 v[44:47], v[156:159], v[180:183], v[44:47]
	v_mfma_f32_16x16x32_bf16 v[36:39], v[164:167], v[180:183], v[36:39]
	v_mfma_f32_16x16x32_bf16 v[28:31], v[156:159], v[188:191], v[28:31]
	v_mfma_f32_16x16x32_bf16 v[20:23], v[164:167], v[188:191], v[20:23]
	v_mfma_f32_16x16x32_bf16 v[12:15], v[156:159], v[198:201], v[12:15]
	v_mfma_f32_16x16x32_bf16 v[4:7], v[164:167], v[198:201], v[4:7]
	s_barrier
	s_add_u32 s26, s26, 0x80080
	s_addc_u32 s27, s27, 0
	s_add_i32 s36, s36, s22
	v_lshl_add_u64 v[152:153], s[26:27], 0, v[130:131]
	s_mov_b32 m0, s36
	s_nop 0
	global_load_lds_dwordx4 v[152:153], off
	v_lshl_add_u64 v[152:153], s[26:27], 0, v[134:135]
	s_add_i32 m0, s36, 0x2000
	s_nop 0
	global_load_lds_dwordx4 v[152:153], off
	s_waitcnt vmcnt(6)
	s_barrier
	v_mfma_f32_16x16x32_bf16 v[56:59], v[202:205], v[168:171], v[56:59]
	v_mfma_f32_16x16x32_bf16 v[48:51], v[210:213], v[168:171], v[48:51]
	v_mfma_f32_16x16x32_bf16 v[40:43], v[202:205], v[176:179], v[40:43]
	v_mfma_f32_16x16x32_bf16 v[32:35], v[210:213], v[176:179], v[32:35]
	v_mfma_f32_16x16x32_bf16 v[24:27], v[202:205], v[184:187], v[24:27]
	v_mfma_f32_16x16x32_bf16 v[16:19], v[210:213], v[184:187], v[16:19]
	v_mfma_f32_16x16x32_bf16 v[8:11], v[202:205], v[192:195], v[8:11]
	v_mfma_f32_16x16x32_bf16 v[0:3], v[210:213], v[192:195], v[0:3]
	v_mfma_f32_16x16x32_bf16 v[56:59], v[206:209], v[172:175], v[56:59]
	v_mfma_f32_16x16x32_bf16 v[48:51], v[214:217], v[172:175], v[48:51]
	v_mfma_f32_16x16x32_bf16 v[40:43], v[206:209], v[180:183], v[40:43]
	v_mfma_f32_16x16x32_bf16 v[32:35], v[214:217], v[180:183], v[32:35]
	v_mfma_f32_16x16x32_bf16 v[24:27], v[206:209], v[188:191], v[24:27]
	v_mfma_f32_16x16x32_bf16 v[16:19], v[214:217], v[188:191], v[16:19]
	v_mfma_f32_16x16x32_bf16 v[8:11], v[206:209], v[198:201], v[8:11]
	v_mfma_f32_16x16x32_bf16 v[0:3], v[214:217], v[198:201], v[0:3]
	s_add_i32 s45, s45, 2
	s_add_u32 s24, s24, 0x100
	s_addc_u32 s25, s25, 0
	s_add_u32 s43, s43, 0x100
	s_addc_u32 s44, s44, 0
	s_cmp_gt_u32 s45, 29
	s_barrier
; __device__ __forceinline__ unsigned pk_bf16(float lo, float hi) { unsigned r; asm volatile("v_cvt_pk_bf16_f32 %0, %1, %2" : "=v"(r) : "v"(lo), "v"(hi)); return r; }
; __device__ __forceinline__ float sigmoidf_(float x) { return __builtin_amdgcn_rcpf(1.0f + __expf(-x)); }
;     __device__ __forceinline__ void operator()(const f32x4 (&acc)[2][2][4][2], const Unit& u, int wr, int wc, int fr, int fq) const {
;         const int row0 = u.pm * 256 + wr * 64 + fr, col0 = u.pn * 128 + wc * 32 + 8 * fq;
;         float rs[2][4];
; #pragma unroll
;         for (int ai = 0; ai < 2; ++ai)
; #pragma unroll
;             for (int m = 0; m < 4; ++m) rs[ai][m] = rowsq[row0 + ai * 128 + m * 16];
; #pragma unroll
;         for (int ai = 0; ai < 2; ++ai)
; #pragma unroll
;             for (int m = 0; m < 4; ++m) {
;                 const int row = row0 + ai * 128 + m * 16;
;                 const float rstd = rsqrtf(rs[ai][m] * (1.0f / D) + RMS_EPS);
;                 f32x4 o[2];
; #pragma unroll
;                 for (int n = 0; n < 2; ++n)
; #pragma unroll
;                     for (int j = 0; j < 4; ++j) { const float gt = acc[ai][0][m][n][j] * rstd, up = acc[ai][1][m][n][j] * rstd; o[n][j] = gt * sigmoidf_(gt) * up; }
;                 u32x4 w; w.x = pk_bf16(o[0][0], o[0][1]); w.y = pk_bf16(o[0][2], o[0][3]); w.z = pk_bf16(o[1][0], o[1][1]); w.w = pk_bf16(o[1][2], o[1][3]);
;                 *(u32x4*)(U + (size_t)row * DFF + col0) = w;
;             }
	s_cbranch_scc0 .LBB0_1209
	s_setprio 0
	v_lshl_add_u32 v154, s18, 8, v144
	v_ashrrev_i32_e32 v155, 31, v154
	v_lshl_add_u64 v[156:157], v[154:155], 2, s[96:97]
	global_load_dword v155, v[156:157], off
	v_or_b32_e32 v168, 16, v154
	v_ashrrev_i32_e32 v169, 31, v168
	v_lshl_add_u64 v[170:171], v[168:169], 2, s[96:97]
	global_load_dword v169, v[170:171], off
	v_mov_b32_e32 v166, v122
	v_or_b32_e32 v122, 48, v154
	v_mov_b32_e32 v160, v124
	v_mov_b32_e32 v167, v114
	v_mov_b32_e32 v114, v123
	v_or_b32_e32 v124, 32, v154
	v_ashrrev_i32_e32 v123, 31, v122
	v_mov_b32_e32 v161, v116
	v_mov_b32_e32 v116, v125
	v_ashrrev_i32_e32 v125, 31, v124
	v_lshl_add_u64 v[172:173], v[122:123], 2, s[96:97]
	v_lshl_add_u64 v[170:171], v[124:125], 2, s[96:97]
	v_mov_b32_e32 v162, v126
	global_load_dword v174, v[156:157], off offset:512
	global_load_dword v153, v[156:157], off offset:576
	global_load_dword v151, v[156:157], off offset:640
	s_nop 0
	global_load_dword v170, v[170:171], off
	s_nop 0
	global_load_dword v171, v[172:173], off
	global_load_dword v126, v[156:157], off offset:704
	v_mov_b32_e32 v165, v112
	v_mov_b32_e32 v112, v121
	v_mov_b32_e32 v163, v118
	v_mov_b32_e32 v118, v127
	v_mov_b32_e32 v164, v120
	v_mov_b64_e32 v[120:121], s[48:49]
	v_add_u32_e32 v152, 0x80, v154
	v_add_u32_e32 v127, 0x90, v154
	v_lshl_or_b32 v158, s42, 7, v146
	v_ashrrev_i32_e32 v159, 31, v158
	s_mov_b32 s42, s8
	s_mov_b32 s18, s10
	s_mov_b64 s[26:27], s[16:17]
	s_mov_b64 s[24:25], s[12:13]
	s_waitcnt vmcnt(0)
	v_fmamk_f32 v123, v155, 0x3a000000, v150
	v_mul_f32_e32 v125, 0x4b800000, v123
	v_cmp_gt_f32_e32 vcc, s40, v123
	s_nop 1
	v_cndmask_b32_e32 v123, v123, v125, vcc
	v_rsq_f32_e32 v155, v123
	v_add_u32_e32 v125, 0xa0, v154
	v_add_u32_e32 v123, 0xb0, v154
	v_mul_f32_e32 v156, 0x45800000, v155
	v_cndmask_b32_e32 v156, v155, v156, vcc
	v_pk_mul_f32 v[116:117], v[116:117], v[156:157] op_sel_hi:[1,0]
	v_pk_mul_f32 v[112:113], v[112:113], v[156:157] op_sel_hi:[1,0]
	v_pk_mul_f32 v[160:161], v[160:161], v[156:157] op_sel_hi:[1,0]
	v_pk_mul_f32 v[162:163], v[162:163], v[156:157] op_sel_hi:[1,0]
	v_pk_mul_f32 v[118:119], v[118:119], v[156:157] op_sel_hi:[1,0]
	v_pk_mul_f32 v[164:165], v[164:165], v[156:157] op_sel_hi:[1,0]
	v_pk_mul_f32 v[166:167], v[166:167], v[156:157] op_sel_hi:[1,0]
	v_pk_mul_f32 v[114:115], v[114:115], v[156:157] op_sel_hi:[1,0]
	v_mul_f32_e32 v156, 0xbfb8aa3b, v117
	v_mul_f32_e32 v175, 0xbfb8aa3b, v113
	v_mul_f32_e32 v155, 0xbfb8aa3b, v161
	v_mul_f32_e32 v157, 0xbfb8aa3b, v163
	v_mul_f32_e32 v172, 0xbfb8aa3b, v119
	v_mul_f32_e32 v173, 0xbfb8aa3b, v165
	v_mul_f32_e32 v176, 0xbfb8aa3b, v167
	v_mul_f32_e32 v177, 0xbfb8aa3b, v115
	v_exp_f32_e32 v156, v156
	v_exp_f32_e32 v175, v175
	v_exp_f32_e32 v155, v155
	v_exp_f32_e32 v157, v157
	v_exp_f32_e32 v172, v172
	v_exp_f32_e32 v173, v173
	v_exp_f32_e32 v176, v176
	v_exp_f32_e32 v177, v177
	v_add_f32_e32 v156, 1.0, v156
	v_add_f32_e32 v175, 1.0, v175
	v_add_f32_e32 v155, 1.0, v155
	v_add_f32_e32 v157, 1.0, v157
	v_add_f32_e32 v172, 1.0, v172
	v_add_f32_e32 v173, 1.0, v173
	v_add_f32_e32 v176, 1.0, v176
	v_add_f32_e32 v177, 1.0, v177
	v_rcp_f32_e32 v156, v156
	v_rcp_f32_e32 v175, v175
	v_rcp_f32_e32 v155, v155
	v_rcp_f32_e32 v157, v157
	v_rcp_f32_e32 v172, v172
	v_rcp_f32_e32 v173, v173
	v_rcp_f32_e32 v176, v176
	v_rcp_f32_e32 v177, v177
	v_mul_f32_e32 v117, v117, v156
	v_mul_f32_e32 v113, v113, v175
	v_mul_f32_e32 v155, v161, v155
	v_mul_f32_e32 v156, v163, v157
	v_mul_f32_e32 v119, v119, v172
	v_mul_f32_e32 v157, v165, v173
	v_mul_f32_e32 v161, v167, v176
	v_mul_f32_e32 v115, v115, v177
	v_mul_f32_e32 v116, v116, v117
	v_mul_f32_e32 v112, v112, v113
	v_mul_f32_e32 v155, v160, v155
	v_mul_f32_e32 v117, v162, v156
	v_mul_f32_e32 v118, v118, v119
	v_mul_f32_e32 v119, v164, v157
	v_mul_f32_e32 v113, v166, v161
	v_mul_f32_e32 v156, v114, v115
	v_cvt_pk_bf16_f32 v114, v155, v116
	v_cvt_pk_bf16_f32 v115, v117, v118
	v_cvt_pk_bf16_f32 v116, v119, v112
	v_fmamk_f32 v112, v169, 0x3a000000, v150
	v_cvt_pk_bf16_f32 v117, v113, v156
	v_mul_f32_e32 v113, 0x4b800000, v112
	v_cmp_gt_f32_e32 vcc, s40, v112
	v_mad_i64_i32 v[118:119], s[4:5], v154, s41, v[120:121]
	s_nop 0
	v_cndmask_b32_e32 v112, v112, v113, vcc
	v_rsq_f32_e32 v155, v112
	v_mov_b32_e32 v156, v104
	v_mov_b32_e32 v157, v108
	v_mov_b32_e32 v108, v105
	v_mul_f32_e32 v154, 0x45800000, v155
	v_cndmask_b32_e32 v154, v155, v154, vcc
	v_pk_mul_f32 v[156:157], v[156:157], v[154:155] op_sel_hi:[1,0]
	v_lshlrev_b64 v[112:113], 1, v[158:159]
	v_mul_f32_e32 v104, 0xbfb8aa3b, v157
	v_exp_f32_e32 v155, v104
	s_nop 0
	v_pk_mul_f32 v[104:105], v[108:109], v[154:155] op_sel_hi:[1,0]
	s_nop 0
	v_mul_f32_e32 v108, 0xbfb8aa3b, v105
	v_exp_f32_e32 v158, v108
	v_lshl_add_u64 v[108:109], v[118:119], 0, v[112:113]
	v_add_f32_e32 v118, 1.0, v155
	v_rcp_f32_e32 v118, v118
	global_store_dwordx4 v[108:109], v[114:117], off
	v_mov_b32_e32 v109, v110
	v_add_f32_e32 v119, 1.0, v158
	v_mul_f32_e32 v108, v157, v118
	v_mul_f32_e32 v114, v156, v108
	v_mov_b32_e32 v108, v106
	v_pk_mul_f32 v[108:109], v[108:109], v[154:155] op_sel_hi:[1,0]
	v_mov_b32_e32 v110, v107
	v_mul_f32_e32 v106, 0xbfb8aa3b, v109
	v_rcp_f32_e32 v119, v119
	v_exp_f32_e32 v115, v106
	v_pk_mul_f32 v[106:107], v[110:111], v[154:155] op_sel_hi:[1,0]
	v_mul_f32_e32 v105, v105, v119
	v_mul_f32_e32 v110, 0xbfb8aa3b, v107
	v_exp_f32_e32 v110, v110
	v_mul_f32_e32 v111, v104, v105
	v_add_f32_e32 v104, 1.0, v115
	v_rcp_f32_e32 v115, v104
	v_add_f32_e32 v104, 1.0, v110
	v_rcp_f32_e32 v110, v104
	v_mov_b32_e32 v104, v96
	v_mov_b32_e32 v105, v100
	v_pk_mul_f32 v[104:105], v[104:105], v[154:155] op_sel_hi:[1,0]
	v_mul_f32_e32 v100, v109, v115
; __device__ __forceinline__ unsigned pk_bf16(float lo, float hi) { unsigned r; asm volatile("v_cvt_pk_bf16_f32 %0, %1, %2" : "=v"(r) : "v"(lo), "v"(hi)); return r; }
; __device__ __forceinline__ float sigmoidf_(float x) { return __builtin_amdgcn_rcpf(1.0f + __expf(-x)); }
;     __device__ __forceinline__ void operator()(const f32x4 (&acc)[2][2][4][2], const Unit& u, int wr, int wc, int fr, int fq) const {
;     ...
;         for (int ai = 0; ai < 2; ++ai)
; #pragma unroll
;             for (int m = 0; m < 4; ++m) {
;                 const int row = row0 + ai * 128 + m * 16;
;                 const float rstd = rsqrtf(rs[ai][m] * (1.0f / D) + RMS_EPS);
;                 f32x4 o[2];
; #pragma unroll
;                 for (int n = 0; n < 2; ++n)
; #pragma unroll
;                     for (int j = 0; j < 4; ++j) { const float gt = acc[ai][0][m][n][j] * rstd, up = acc[ai][1][m][n][j] * rstd; o[n][j] = gt * sigmoidf_(gt) * up; }
;                 u32x4 w; w.x = pk_bf16(o[0][0], o[0][1]); w.y = pk_bf16(o[0][2], o[0][3]); w.z = pk_bf16(o[1][0], o[1][1]); w.w = pk_bf16(o[1][2], o[1][3]);
;                 *(u32x4*)(U + (size_t)row * DFF + col0) = w;
;             }
	v_mul_f32_e32 v96, 0xbfb8aa3b, v105
	v_exp_f32_e32 v96, v96
	v_mul_f32_e32 v108, v108, v100
	v_mov_b32_e32 v100, v97
	v_mul_f32_e32 v107, v107, v110
	v_add_f32_e32 v96, 1.0, v96
	v_rcp_f32_e32 v109, v96
	v_pk_mul_f32 v[96:97], v[100:101], v[154:155] op_sel_hi:[1,0]
	v_mul_f32_e32 v106, v106, v107
	v_mul_f32_e32 v100, 0xbfb8aa3b, v97
	v_exp_f32_e32 v100, v100
	v_mul_f32_e32 v101, v105, v109
	v_mul_f32_e32 v104, v104, v101
	v_mov_b32_e32 v101, v102
	v_add_f32_e32 v100, 1.0, v100
	v_rcp_f32_e32 v105, v100
	v_mov_b32_e32 v100, v98
	v_pk_mul_f32 v[100:101], v[100:101], v[154:155] op_sel_hi:[1,0]
	v_mov_b32_e32 v102, v99
	v_mul_f32_e32 v98, 0xbfb8aa3b, v101
	v_exp_f32_e32 v107, v98
	v_pk_mul_f32 v[98:99], v[102:103], v[154:155] op_sel_hi:[1,0]
	v_mul_f32_e32 v97, v97, v105
	v_mul_f32_e32 v102, 0xbfb8aa3b, v99
	v_exp_f32_e32 v102, v102
	v_add_f32_e32 v103, 1.0, v107
	v_rcp_f32_e32 v103, v103
	v_mul_f32_e32 v105, v96, v97
	v_add_f32_e32 v102, 1.0, v102
	v_rcp_f32_e32 v102, v102
	v_mul_f32_e32 v96, v101, v103
	v_fmamk_f32 v101, v170, 0x3a000000, v150
	v_mul_f32_e32 v100, v100, v96
	v_mul_f32_e32 v96, v99, v102
	v_mul_f32_e32 v102, 0x4b800000, v101
	v_cmp_gt_f32_e32 vcc, s40, v101
	v_mul_f32_e32 v99, v98, v96
	v_cvt_pk_bf16_f32 v96, v114, v111
	v_cvt_pk_bf16_f32 v97, v108, v106
	v_cvt_pk_bf16_f32 v98, v104, v105
	v_mov_b32_e32 v104, v88
	v_cndmask_b32_e32 v101, v101, v102, vcc
	v_rsq_f32_e32 v102, v101
	v_mov_b32_e32 v105, v92
	v_mov_b32_e32 v92, v89
	v_cvt_pk_bf16_f32 v99, v100, v99
	v_mul_f32_e32 v103, 0x45800000, v102
	v_cndmask_b32_e32 v102, v102, v103, vcc
	v_pk_mul_f32 v[104:105], v[104:105], v[102:103] op_sel_hi:[1,0]
	v_mad_i64_i32 v[100:101], s[4:5], v168, s41, v[120:121]
	v_mul_f32_e32 v88, 0xbfb8aa3b, v105
	v_exp_f32_e32 v103, v88
	s_nop 0
	v_pk_mul_f32 v[88:89], v[92:93], v[102:103] op_sel_hi:[1,0]
	s_nop 0
	v_mul_f32_e32 v92, 0xbfb8aa3b, v89
	v_exp_f32_e32 v106, v92
	v_lshl_add_u64 v[92:93], v[100:101], 0, v[112:113]
	v_add_f32_e32 v100, 1.0, v103
	v_rcp_f32_e32 v100, v100
	global_store_dwordx4 v[92:93], v[96:99], off
	v_mov_b32_e32 v93, v94
	v_add_f32_e32 v101, 1.0, v106
	v_mul_f32_e32 v92, v105, v100
	v_mul_f32_e32 v96, v104, v92
	v_mov_b32_e32 v92, v90
	v_pk_mul_f32 v[92:93], v[92:93], v[102:103] op_sel_hi:[1,0]
	v_mov_b32_e32 v94, v91
	v_mul_f32_e32 v90, 0xbfb8aa3b, v93
	v_rcp_f32_e32 v101, v101
	v_exp_f32_e32 v97, v90
	v_pk_mul_f32 v[90:91], v[94:95], v[102:103] op_sel_hi:[1,0]
	v_mul_f32_e32 v89, v89, v101
	v_mul_f32_e32 v94, 0xbfb8aa3b, v91
	v_exp_f32_e32 v94, v94
	v_mul_f32_e32 v95, v88, v89
	v_add_f32_e32 v88, 1.0, v97
	v_rcp_f32_e32 v97, v88
	v_add_f32_e32 v88, 1.0, v94
	v_rcp_f32_e32 v94, v88
	v_mov_b32_e32 v88, v80
	v_mov_b32_e32 v89, v84
	v_pk_mul_f32 v[88:89], v[88:89], v[102:103] op_sel_hi:[1,0]
	v_mul_f32_e32 v84, v93, v97
	v_mul_f32_e32 v80, 0xbfb8aa3b, v89
	v_exp_f32_e32 v80, v80
	v_mul_f32_e32 v92, v92, v84
	v_mov_b32_e32 v84, v81
	v_mul_f32_e32 v91, v91, v94
	v_add_f32_e32 v80, 1.0, v80
	v_rcp_f32_e32 v93, v80
	v_pk_mul_f32 v[80:81], v[84:85], v[102:103] op_sel_hi:[1,0]
	v_mul_f32_e32 v90, v90, v91
	v_mul_f32_e32 v84, 0xbfb8aa3b, v81
	v_exp_f32_e32 v84, v84
	v_mul_f32_e32 v85, v89, v93
	v_mul_f32_e32 v88, v88, v85
	v_mov_b32_e32 v85, v86
	v_add_f32_e32 v84, 1.0, v84
	v_rcp_f32_e32 v89, v84
	v_mov_b32_e32 v84, v82
	v_pk_mul_f32 v[84:85], v[84:85], v[102:103] op_sel_hi:[1,0]
	v_mov_b32_e32 v86, v83
	v_mul_f32_e32 v82, 0xbfb8aa3b, v85
	v_exp_f32_e32 v91, v82
	v_pk_mul_f32 v[82:83], v[86:87], v[102:103] op_sel_hi:[1,0]
	v_mul_f32_e32 v81, v81, v89
	v_mul_f32_e32 v86, 0xbfb8aa3b, v83
	v_exp_f32_e32 v86, v86
	v_add_f32_e32 v87, 1.0, v91
	v_rcp_f32_e32 v87, v87
	v_mul_f32_e32 v89, v80, v81
	v_add_f32_e32 v86, 1.0, v86
	v_rcp_f32_e32 v86, v86
	v_mul_f32_e32 v80, v85, v87
	v_fmamk_f32 v85, v171, 0x3a000000, v150
	v_mul_f32_e32 v84, v84, v80
	v_mul_f32_e32 v80, v83, v86
	v_mul_f32_e32 v86, 0x4b800000, v85
	v_cmp_gt_f32_e32 vcc, s40, v85
	v_mul_f32_e32 v83, v82, v80
	v_cvt_pk_bf16_f32 v80, v96, v95
	v_cvt_pk_bf16_f32 v81, v92, v90
	v_cvt_pk_bf16_f32 v82, v88, v89
	v_mov_b32_e32 v88, v72
	v_cndmask_b32_e32 v85, v85, v86, vcc
	v_rsq_f32_e32 v86, v85
	v_mov_b32_e32 v89, v76
	v_mov_b32_e32 v76, v73
	v_cvt_pk_bf16_f32 v83, v84, v83
	v_mul_f32_e32 v87, 0x45800000, v86
	v_cndmask_b32_e32 v86, v86, v87, vcc
	v_pk_mul_f32 v[88:89], v[88:89], v[86:87] op_sel_hi:[1,0]
	v_mad_i64_i32 v[84:85], s[4:5], v124, s41, v[120:121]
	v_mul_f32_e32 v72, 0xbfb8aa3b, v89
	v_exp_f32_e32 v87, v72
	s_nop 0
	v_pk_mul_f32 v[72:73], v[76:77], v[86:87] op_sel_hi:[1,0]
	s_nop 0
	v_mul_f32_e32 v76, 0xbfb8aa3b, v73
	v_exp_f32_e32 v90, v76
	v_lshl_add_u64 v[76:77], v[84:85], 0, v[112:113]
	v_add_f32_e32 v84, 1.0, v87
	v_rcp_f32_e32 v84, v84
	global_store_dwordx4 v[76:77], v[80:83], off
	v_mov_b32_e32 v77, v78
	v_add_f32_e32 v85, 1.0, v90
	v_mul_f32_e32 v76, v89, v84
	v_mul_f32_e32 v80, v88, v76
	v_mov_b32_e32 v76, v74
	v_pk_mul_f32 v[76:77], v[76:77], v[86:87] op_sel_hi:[1,0]
	v_mov_b32_e32 v78, v75
	v_mul_f32_e32 v74, 0xbfb8aa3b, v77
	v_rcp_f32_e32 v85, v85
	v_exp_f32_e32 v81, v74
	v_pk_mul_f32 v[74:75], v[78:79], v[86:87] op_sel_hi:[1,0]
	v_mul_f32_e32 v73, v73, v85
	v_mul_f32_e32 v78, 0xbfb8aa3b, v75
	v_exp_f32_e32 v78, v78
	v_mul_f32_e32 v79, v72, v73
	v_add_f32_e32 v72, 1.0, v81
	v_rcp_f32_e32 v81, v72
	v_add_f32_e32 v72, 1.0, v78
	v_rcp_f32_e32 v78, v72
	v_mov_b32_e32 v72, v64
	v_mov_b32_e32 v73, v68
	v_pk_mul_f32 v[72:73], v[72:73], v[86:87] op_sel_hi:[1,0]
	v_mul_f32_e32 v68, v77, v81
	v_mul_f32_e32 v64, 0xbfb8aa3b, v73
	v_exp_f32_e32 v64, v64
	v_mul_f32_e32 v76, v76, v68
	v_mov_b32_e32 v68, v65
	v_mul_f32_e32 v75, v75, v78
	v_add_f32_e32 v64, 1.0, v64
; __device__ __forceinline__ unsigned pk_bf16(float lo, float hi) { unsigned r; asm volatile("v_cvt_pk_bf16_f32 %0, %1, %2" : "=v"(r) : "v"(lo), "v"(hi)); return r; }
; __device__ __forceinline__ float sigmoidf_(float x) { return __builtin_amdgcn_rcpf(1.0f + __expf(-x)); }
;     __device__ __forceinline__ void operator()(const f32x4 (&acc)[2][2][4][2], const Unit& u, int wr, int wc, int fr, int fq) const {
;     ...
;         for (int ai = 0; ai < 2; ++ai)
; #pragma unroll
;             for (int m = 0; m < 4; ++m) {
;                 const int row = row0 + ai * 128 + m * 16;
;                 const float rstd = rsqrtf(rs[ai][m] * (1.0f / D) + RMS_EPS);
;                 f32x4 o[2];
; #pragma unroll
;                 for (int n = 0; n < 2; ++n)
; #pragma unroll
;                     for (int j = 0; j < 4; ++j) { const float gt = acc[ai][0][m][n][j] * rstd, up = acc[ai][1][m][n][j] * rstd; o[n][j] = gt * sigmoidf_(gt) * up; }
;                 u32x4 w; w.x = pk_bf16(o[0][0], o[0][1]); w.y = pk_bf16(o[0][2], o[0][3]); w.z = pk_bf16(o[1][0], o[1][1]); w.w = pk_bf16(o[1][2], o[1][3]);
;                 *(u32x4*)(U + (size_t)row * DFF + col0) = w;
;             }
	v_rcp_f32_e32 v77, v64
	v_pk_mul_f32 v[64:65], v[68:69], v[86:87] op_sel_hi:[1,0]
	v_mul_f32_e32 v74, v74, v75
	v_mul_f32_e32 v68, 0xbfb8aa3b, v65
	v_exp_f32_e32 v68, v68
	v_mul_f32_e32 v69, v73, v77
	v_mul_f32_e32 v72, v72, v69
	v_mov_b32_e32 v69, v70
	v_add_f32_e32 v68, 1.0, v68
	v_rcp_f32_e32 v73, v68
	v_mov_b32_e32 v68, v66
	v_pk_mul_f32 v[68:69], v[68:69], v[86:87] op_sel_hi:[1,0]
	v_mov_b32_e32 v70, v67
	v_mul_f32_e32 v66, 0xbfb8aa3b, v69
	v_exp_f32_e32 v75, v66
	v_pk_mul_f32 v[66:67], v[70:71], v[86:87] op_sel_hi:[1,0]
	v_mul_f32_e32 v65, v65, v73
	v_mul_f32_e32 v70, 0xbfb8aa3b, v67
	v_exp_f32_e32 v70, v70
	v_add_f32_e32 v71, 1.0, v75
	v_rcp_f32_e32 v71, v71
	v_mul_f32_e32 v73, v64, v65
	v_add_f32_e32 v70, 1.0, v70
	v_rcp_f32_e32 v70, v70
	v_mul_f32_e32 v64, v69, v71
	v_fmamk_f32 v69, v174, 0x3a000000, v150
	v_mul_f32_e32 v68, v68, v64
	v_mul_f32_e32 v64, v67, v70
	v_mul_f32_e32 v70, 0x4b800000, v69
	v_cmp_gt_f32_e32 vcc, s40, v69
	v_mul_f32_e32 v67, v66, v64
	v_cvt_pk_bf16_f32 v64, v80, v79
	v_cvt_pk_bf16_f32 v65, v76, v74
	v_cvt_pk_bf16_f32 v66, v72, v73
	v_mov_b32_e32 v72, v56
	v_cndmask_b32_e32 v69, v69, v70, vcc
	v_rsq_f32_e32 v70, v69
	v_mov_b32_e32 v73, v60
	v_mov_b32_e32 v60, v57
	v_cvt_pk_bf16_f32 v67, v68, v67
	v_mul_f32_e32 v71, 0x45800000, v70
	v_cndmask_b32_e32 v70, v70, v71, vcc
	v_pk_mul_f32 v[72:73], v[72:73], v[70:71] op_sel_hi:[1,0]
	v_mad_i64_i32 v[68:69], s[4:5], v122, s41, v[120:121]
	v_mul_f32_e32 v56, 0xbfb8aa3b, v73
	v_exp_f32_e32 v71, v56
	s_nop 0
	v_pk_mul_f32 v[56:57], v[60:61], v[70:71] op_sel_hi:[1,0]
	s_nop 0
	v_mul_f32_e32 v60, 0xbfb8aa3b, v57
	v_exp_f32_e32 v74, v60
	v_lshl_add_u64 v[60:61], v[68:69], 0, v[112:113]
	v_add_f32_e32 v68, 1.0, v71
	v_rcp_f32_e32 v68, v68
	global_store_dwordx4 v[60:61], v[64:67], off
	v_mov_b32_e32 v61, v62
	v_add_f32_e32 v69, 1.0, v74
	v_mul_f32_e32 v60, v73, v68
	v_mul_f32_e32 v64, v72, v60
	v_mov_b32_e32 v60, v58
	v_pk_mul_f32 v[60:61], v[60:61], v[70:71] op_sel_hi:[1,0]
	v_mov_b32_e32 v62, v59
	v_mul_f32_e32 v58, 0xbfb8aa3b, v61
	v_rcp_f32_e32 v69, v69
	v_exp_f32_e32 v65, v58
	v_pk_mul_f32 v[58:59], v[62:63], v[70:71] op_sel_hi:[1,0]
	v_mul_f32_e32 v57, v57, v69
	v_mul_f32_e32 v62, 0xbfb8aa3b, v59
	v_exp_f32_e32 v62, v62
	v_mul_f32_e32 v63, v56, v57
	v_add_f32_e32 v56, 1.0, v65
	v_rcp_f32_e32 v65, v56
	v_add_f32_e32 v56, 1.0, v62
	v_rcp_f32_e32 v62, v56
	v_mov_b32_e32 v56, v48
	v_mov_b32_e32 v57, v52
	v_pk_mul_f32 v[56:57], v[56:57], v[70:71] op_sel_hi:[1,0]
	v_mul_f32_e32 v52, v61, v65
	v_mul_f32_e32 v48, 0xbfb8aa3b, v57
	v_exp_f32_e32 v48, v48
	v_mul_f32_e32 v60, v60, v52
	v_mov_b32_e32 v52, v49
	v_mul_f32_e32 v59, v59, v62
	v_add_f32_e32 v48, 1.0, v48
	v_rcp_f32_e32 v61, v48
	v_pk_mul_f32 v[48:49], v[52:53], v[70:71] op_sel_hi:[1,0]
	v_mul_f32_e32 v58, v58, v59
	v_mul_f32_e32 v52, 0xbfb8aa3b, v49
	v_exp_f32_e32 v52, v52
	v_mul_f32_e32 v53, v57, v61
	v_mul_f32_e32 v56, v56, v53
	v_mov_b32_e32 v53, v54
	v_add_f32_e32 v52, 1.0, v52
	v_rcp_f32_e32 v57, v52
	v_mov_b32_e32 v52, v50
	v_pk_mul_f32 v[52:53], v[52:53], v[70:71] op_sel_hi:[1,0]
	v_mov_b32_e32 v54, v51
	v_mul_f32_e32 v50, 0xbfb8aa3b, v53
	v_exp_f32_e32 v59, v50
	v_pk_mul_f32 v[50:51], v[54:55], v[70:71] op_sel_hi:[1,0]
	v_mul_f32_e32 v49, v49, v57
	v_mul_f32_e32 v54, 0xbfb8aa3b, v51
	v_exp_f32_e32 v54, v54
	v_add_f32_e32 v55, 1.0, v59
	v_rcp_f32_e32 v55, v55
	v_mul_f32_e32 v57, v48, v49
	v_add_f32_e32 v54, 1.0, v54
	v_rcp_f32_e32 v54, v54
	v_mul_f32_e32 v48, v53, v55
	v_fmamk_f32 v53, v153, 0x3a000000, v150
	v_mul_f32_e32 v52, v52, v48
	v_mul_f32_e32 v48, v51, v54
	v_mul_f32_e32 v54, 0x4b800000, v53
	v_cmp_gt_f32_e32 vcc, s40, v53
	v_mul_f32_e32 v51, v50, v48
	v_cvt_pk_bf16_f32 v48, v64, v63
	v_cvt_pk_bf16_f32 v49, v60, v58
	v_cvt_pk_bf16_f32 v50, v56, v57
	v_mov_b32_e32 v56, v40
	v_cndmask_b32_e32 v53, v53, v54, vcc
	v_rsq_f32_e32 v54, v53
	v_mov_b32_e32 v57, v44
	v_mov_b32_e32 v44, v41
	v_cvt_pk_bf16_f32 v51, v52, v51
	v_mul_f32_e32 v55, 0x45800000, v54
	v_cndmask_b32_e32 v54, v54, v55, vcc
	v_pk_mul_f32 v[56:57], v[56:57], v[54:55] op_sel_hi:[1,0]
	v_mad_i64_i32 v[52:53], s[4:5], v152, s41, v[120:121]
	v_mul_f32_e32 v40, 0xbfb8aa3b, v57
	v_exp_f32_e32 v55, v40
	s_nop 0
	v_pk_mul_f32 v[40:41], v[44:45], v[54:55] op_sel_hi:[1,0]
	s_nop 0
	v_mul_f32_e32 v44, 0xbfb8aa3b, v41
	v_exp_f32_e32 v58, v44
	v_lshl_add_u64 v[44:45], v[52:53], 0, v[112:113]
	v_add_f32_e32 v52, 1.0, v55
	v_rcp_f32_e32 v52, v52
	global_store_dwordx4 v[44:45], v[48:51], off
	v_mov_b32_e32 v45, v46
	v_add_f32_e32 v53, 1.0, v58
	v_mul_f32_e32 v44, v57, v52
	v_mul_f32_e32 v48, v56, v44
	v_mov_b32_e32 v44, v42
	v_pk_mul_f32 v[44:45], v[44:45], v[54:55] op_sel_hi:[1,0]
	v_mov_b32_e32 v46, v43
	v_mul_f32_e32 v42, 0xbfb8aa3b, v45
	v_rcp_f32_e32 v53, v53
	v_exp_f32_e32 v49, v42
	v_pk_mul_f32 v[42:43], v[46:47], v[54:55] op_sel_hi:[1,0]
	v_mul_f32_e32 v41, v41, v53
	v_mul_f32_e32 v46, 0xbfb8aa3b, v43
	v_exp_f32_e32 v46, v46
	v_mul_f32_e32 v47, v40, v41
	v_add_f32_e32 v40, 1.0, v49
	v_rcp_f32_e32 v49, v40
	v_add_f32_e32 v40, 1.0, v46
	v_rcp_f32_e32 v46, v40
	v_mov_b32_e32 v40, v32
	v_mov_b32_e32 v41, v36
	v_pk_mul_f32 v[40:41], v[40:41], v[54:55] op_sel_hi:[1,0]
	v_mul_f32_e32 v36, v45, v49
	v_mul_f32_e32 v32, 0xbfb8aa3b, v41
	v_exp_f32_e32 v32, v32
	v_mul_f32_e32 v44, v44, v36
	v_mov_b32_e32 v36, v33
	v_mul_f32_e32 v43, v43, v46
	v_add_f32_e32 v32, 1.0, v32
	v_rcp_f32_e32 v45, v32
	v_pk_mul_f32 v[32:33], v[36:37], v[54:55] op_sel_hi:[1,0]
	v_mul_f32_e32 v42, v42, v43
	v_mul_f32_e32 v36, 0xbfb8aa3b, v33
	v_exp_f32_e32 v36, v36
	v_mul_f32_e32 v37, v41, v45
	v_mul_f32_e32 v40, v40, v37
	v_mov_b32_e32 v37, v38
	v_add_f32_e32 v36, 1.0, v36
; __device__ __forceinline__ unsigned pk_bf16(float lo, float hi) { unsigned r; asm volatile("v_cvt_pk_bf16_f32 %0, %1, %2" : "=v"(r) : "v"(lo), "v"(hi)); return r; }
; __device__ __forceinline__ float sigmoidf_(float x) { return __builtin_amdgcn_rcpf(1.0f + __expf(-x)); }
; template <class Epi, class Sched>
; __device__ __forceinline__ void gemm_phase(LAS unsigned char* lds, const Gemm g, const Sched& S, const Epi& E) {
;     ...
;         if (!has_next) break;
; #pragma unroll
;         for (int a = 0; a < 2; ++a)
; #pragma unroll
;             for (int b = 0; b < 2; ++b)
; #pragma unroll
;                 for (int m = 0; m < 4; ++m)
; #pragma unroll
;                     for (int n = 0; n < 2; ++n) acc[a][b][m][n] = (f32x4){0.f, 0.f, 0.f, 0.f};
;         cur = nxt; cA = nA; cB = nB; ++ui;
;     __device__ __forceinline__ void operator()(const f32x4 (&acc)[2][2][4][2], const Unit& u, int wr, int wc, int fr, int fq) const {
;     ...
;         for (int ai = 0; ai < 2; ++ai)
; #pragma unroll
;             for (int m = 0; m < 4; ++m) {
;                 const int row = row0 + ai * 128 + m * 16;
;                 const float rstd = rsqrtf(rs[ai][m] * (1.0f / D) + RMS_EPS);
;                 f32x4 o[2];
; #pragma unroll
;                 for (int n = 0; n < 2; ++n)
; #pragma unroll
;                     for (int j = 0; j < 4; ++j) { const float gt = acc[ai][0][m][n][j] * rstd, up = acc[ai][1][m][n][j] * rstd; o[n][j] = gt * sigmoidf_(gt) * up; }
;                 u32x4 w; w.x = pk_bf16(o[0][0], o[0][1]); w.y = pk_bf16(o[0][2], o[0][3]); w.z = pk_bf16(o[1][0], o[1][1]); w.w = pk_bf16(o[1][2], o[1][3]);
;                 *(u32x4*)(U + (size_t)row * DFF + col0) = w;
;             }
	v_rcp_f32_e32 v41, v36
	v_mov_b32_e32 v36, v34
	v_pk_mul_f32 v[36:37], v[36:37], v[54:55] op_sel_hi:[1,0]
	v_mov_b32_e32 v38, v35
	v_mul_f32_e32 v34, 0xbfb8aa3b, v37
	v_exp_f32_e32 v43, v34
	v_pk_mul_f32 v[34:35], v[38:39], v[54:55] op_sel_hi:[1,0]
	v_mul_f32_e32 v33, v33, v41
	v_mul_f32_e32 v38, 0xbfb8aa3b, v35
	v_exp_f32_e32 v38, v38
	v_add_f32_e32 v39, 1.0, v43
	v_rcp_f32_e32 v39, v39
	v_mul_f32_e32 v41, v32, v33
	v_add_f32_e32 v38, 1.0, v38
	v_rcp_f32_e32 v38, v38
	v_mul_f32_e32 v32, v37, v39
	v_fmamk_f32 v37, v151, 0x3a000000, v150
	v_mul_f32_e32 v36, v36, v32
	v_mul_f32_e32 v32, v35, v38
	v_mul_f32_e32 v38, 0x4b800000, v37
	v_cmp_gt_f32_e32 vcc, s40, v37
	v_mul_f32_e32 v35, v34, v32
	v_cvt_pk_bf16_f32 v32, v48, v47
	v_cvt_pk_bf16_f32 v33, v44, v42
	v_cvt_pk_bf16_f32 v34, v40, v41
	v_mov_b32_e32 v40, v24
	v_cndmask_b32_e32 v37, v37, v38, vcc
	v_rsq_f32_e32 v38, v37
	v_mov_b32_e32 v41, v28
	v_mov_b32_e32 v28, v25
	v_cvt_pk_bf16_f32 v35, v36, v35
	v_mul_f32_e32 v39, 0x45800000, v38
	v_cndmask_b32_e32 v38, v38, v39, vcc
	v_pk_mul_f32 v[40:41], v[40:41], v[38:39] op_sel_hi:[1,0]
	v_mad_i64_i32 v[36:37], s[4:5], v127, s41, v[120:121]
	v_mul_f32_e32 v24, 0xbfb8aa3b, v41
	v_exp_f32_e32 v39, v24
	s_nop 0
	v_pk_mul_f32 v[24:25], v[28:29], v[38:39] op_sel_hi:[1,0]
	s_nop 0
	v_mul_f32_e32 v28, 0xbfb8aa3b, v25
	v_exp_f32_e32 v42, v28
	v_lshl_add_u64 v[28:29], v[36:37], 0, v[112:113]
	v_add_f32_e32 v36, 1.0, v39
	v_rcp_f32_e32 v36, v36
	global_store_dwordx4 v[28:29], v[32:35], off
	v_mov_b32_e32 v29, v30
	v_add_f32_e32 v37, 1.0, v42
	v_mul_f32_e32 v28, v41, v36
	v_mul_f32_e32 v32, v40, v28
	v_mov_b32_e32 v28, v26
	v_pk_mul_f32 v[28:29], v[28:29], v[38:39] op_sel_hi:[1,0]
	v_mov_b32_e32 v30, v27
	v_mul_f32_e32 v26, 0xbfb8aa3b, v29
	v_rcp_f32_e32 v37, v37
	v_exp_f32_e32 v33, v26
	v_pk_mul_f32 v[26:27], v[30:31], v[38:39] op_sel_hi:[1,0]
	v_mul_f32_e32 v25, v25, v37
	v_mul_f32_e32 v30, 0xbfb8aa3b, v27
	v_exp_f32_e32 v30, v30
	v_mul_f32_e32 v31, v24, v25
	v_add_f32_e32 v24, 1.0, v33
	v_rcp_f32_e32 v33, v24
	v_add_f32_e32 v24, 1.0, v30
	v_rcp_f32_e32 v30, v24
	v_mov_b32_e32 v24, v16
	v_mov_b32_e32 v25, v20
	v_pk_mul_f32 v[24:25], v[24:25], v[38:39] op_sel_hi:[1,0]
	v_mul_f32_e32 v20, v29, v33
	v_mul_f32_e32 v16, 0xbfb8aa3b, v25
	v_exp_f32_e32 v16, v16
	v_mul_f32_e32 v28, v28, v20
	v_mov_b32_e32 v20, v17
	v_mul_f32_e32 v27, v27, v30
	v_add_f32_e32 v16, 1.0, v16
	v_rcp_f32_e32 v29, v16
	v_pk_mul_f32 v[16:17], v[20:21], v[38:39] op_sel_hi:[1,0]
	v_mul_f32_e32 v26, v26, v27
	v_mul_f32_e32 v20, 0xbfb8aa3b, v17
	v_exp_f32_e32 v20, v20
	v_mul_f32_e32 v21, v25, v29
	v_mul_f32_e32 v24, v24, v21
	v_mov_b32_e32 v21, v22
	v_add_f32_e32 v20, 1.0, v20
	v_rcp_f32_e32 v25, v20
	v_mov_b32_e32 v20, v18
	v_pk_mul_f32 v[20:21], v[20:21], v[38:39] op_sel_hi:[1,0]
	v_mov_b32_e32 v22, v19
	v_mul_f32_e32 v18, 0xbfb8aa3b, v21
	v_exp_f32_e32 v27, v18
	v_pk_mul_f32 v[18:19], v[22:23], v[38:39] op_sel_hi:[1,0]
	v_mul_f32_e32 v17, v17, v25
	v_mul_f32_e32 v22, 0xbfb8aa3b, v19
	v_exp_f32_e32 v22, v22
	v_add_f32_e32 v23, 1.0, v27
	v_rcp_f32_e32 v23, v23
	v_mul_f32_e32 v25, v16, v17
	v_add_f32_e32 v22, 1.0, v22
	v_rcp_f32_e32 v22, v22
	v_mul_f32_e32 v16, v21, v23
	v_fmamk_f32 v21, v126, 0x3a000000, v150
	v_mul_f32_e32 v20, v20, v16
	v_mul_f32_e32 v16, v19, v22
	v_mul_f32_e32 v22, 0x4b800000, v21
	v_cmp_gt_f32_e32 vcc, s40, v21
	v_mul_f32_e32 v19, v18, v16
	v_cvt_pk_bf16_f32 v16, v32, v31
	v_cvt_pk_bf16_f32 v17, v28, v26
	v_cvt_pk_bf16_f32 v18, v24, v25
	v_mov_b32_e32 v24, v8
	v_cndmask_b32_e32 v21, v21, v22, vcc
	v_rsq_f32_e32 v22, v21
	v_mov_b32_e32 v25, v12
	v_mov_b32_e32 v12, v9
	v_cvt_pk_bf16_f32 v19, v20, v19
	v_mul_f32_e32 v23, 0x45800000, v22
	v_cndmask_b32_e32 v22, v22, v23, vcc
	v_pk_mul_f32 v[24:25], v[24:25], v[22:23] op_sel_hi:[1,0]
	v_mad_i64_i32 v[20:21], s[4:5], v125, s41, v[120:121]
	v_mul_f32_e32 v8, 0xbfb8aa3b, v25
	v_exp_f32_e32 v23, v8
	s_and_b64 vcc, exec, s[0:1]
	v_pk_mul_f32 v[8:9], v[12:13], v[22:23] op_sel_hi:[1,0]
	s_nop 0
	v_mul_f32_e32 v12, 0xbfb8aa3b, v9
	v_exp_f32_e32 v26, v12
	v_lshl_add_u64 v[12:13], v[20:21], 0, v[112:113]
	v_add_f32_e32 v20, 1.0, v23
	v_rcp_f32_e32 v20, v20
	global_store_dwordx4 v[12:13], v[16:19], off
	v_mov_b32_e32 v13, v14
	v_add_f32_e32 v21, 1.0, v26
	v_mul_f32_e32 v12, v25, v20
	v_mul_f32_e32 v16, v24, v12
	v_mov_b32_e32 v12, v10
	v_pk_mul_f32 v[12:13], v[12:13], v[22:23] op_sel_hi:[1,0]
	v_mov_b32_e32 v14, v11
	v_mul_f32_e32 v10, 0xbfb8aa3b, v13
	v_rcp_f32_e32 v21, v21
	v_exp_f32_e32 v17, v10
	v_pk_mul_f32 v[10:11], v[14:15], v[22:23] op_sel_hi:[1,0]
	v_mul_f32_e32 v9, v9, v21
	v_mul_f32_e32 v14, 0xbfb8aa3b, v11
	v_exp_f32_e32 v14, v14
	v_mul_f32_e32 v15, v8, v9
	v_add_f32_e32 v8, 1.0, v17
	v_rcp_f32_e32 v17, v8
	v_add_f32_e32 v8, 1.0, v14
	v_rcp_f32_e32 v14, v8
	v_mov_b32_e32 v8, v0
	v_mov_b32_e32 v9, v4
	v_pk_mul_f32 v[8:9], v[8:9], v[22:23] op_sel_hi:[1,0]
	v_mul_f32_e32 v4, v13, v17
	v_mul_f32_e32 v0, 0xbfb8aa3b, v9
	v_exp_f32_e32 v0, v0
	v_mul_f32_e32 v12, v12, v4
	v_mov_b32_e32 v4, v1
	v_mul_f32_e32 v11, v11, v14
	v_add_f32_e32 v0, 1.0, v0
	v_rcp_f32_e32 v13, v0
	v_pk_mul_f32 v[0:1], v[4:5], v[22:23] op_sel_hi:[1,0]
	v_mul_f32_e32 v10, v10, v11
	v_mul_f32_e32 v4, 0xbfb8aa3b, v1
	v_exp_f32_e32 v4, v4
	v_mul_f32_e32 v5, v9, v13
	v_mul_f32_e32 v8, v8, v5
	v_mov_b32_e32 v5, v6
	v_add_f32_e32 v4, 1.0, v4
	v_rcp_f32_e32 v9, v4
	v_mov_b32_e32 v4, v2
	v_pk_mul_f32 v[4:5], v[4:5], v[22:23] op_sel_hi:[1,0]
	v_mov_b32_e32 v6, v3
	v_mul_f32_e32 v2, 0xbfb8aa3b, v5
	v_exp_f32_e32 v11, v2
	v_pk_mul_f32 v[2:3], v[6:7], v[22:23] op_sel_hi:[1,0]
	v_mul_f32_e32 v1, v1, v9
	v_mul_f32_e32 v6, 0xbfb8aa3b, v3
	v_exp_f32_e32 v6, v6
	v_add_f32_e32 v7, 1.0, v11
	v_rcp_f32_e32 v7, v7
	v_mul_f32_e32 v9, v0, v1
	v_add_f32_e32 v6, 1.0, v6
	v_rcp_f32_e32 v6, v6
	v_mul_f32_e32 v0, v5, v7
	v_mul_f32_e32 v4, v4, v0
	v_mul_f32_e32 v0, v3, v6
	v_mul_f32_e32 v3, v2, v0
	v_cvt_pk_bf16_f32 v0, v16, v15
	v_cvt_pk_bf16_f32 v1, v12, v10
	v_cvt_pk_bf16_f32 v2, v8, v9
	v_cvt_pk_bf16_f32 v3, v4, v3
	v_mad_i64_i32 v[4:5], s[4:5], v123, s41, v[120:121]
	v_lshl_add_u64 v[4:5], v[4:5], 0, v[112:113]
	global_store_dwordx4 v[4:5], v[0:3], off
	s_cbranch_vccz .LBB0_1202
	s_waitcnt vmcnt(0)
	s_cmpk_gt_u32 s14, 0xff
	s_cbranch_scc1 .LBB0_1213
	s_barrier
